# MLA key-tile loop unrolled x2 with score-register ping-pong (16 v_mov_b64 per tile removed); all 12 K-fragment LDS reads issued up front with counted lgkmcnt waits
# speedup vs baseline: 1.0390x; 1.0102x over previous
.LBB0_445:
	s_andn2_saveexec_b64 s[86:87], s[86:87]
	s_cbranch_execz .LBB0_456
	v_mfma_f32_32x32x16_bf16 v[80:95], v[112:115], v[152:155], 0
	s_and_b32 s18, s72, 0x4000
	v_or_b32_e32 v173, s18, v194
	v_or_b32_e32 v224, 0x2000, v173
	v_add_u32_e32 v96, v173, v186
	v_add_u32_e32 v97, v224, v186
	v_add_u32_e32 v98, v173, v184
	v_add_u32_e32 v99, v224, v184
	v_add_u32_e32 v100, v173, v183
	v_add_u32_e32 v101, v224, v183
	v_add_u32_e32 v225, v173, v191
	v_add_u32_e32 v226, v224, v191
	v_add_u32_e32 v227, v173, v190
	v_add_u32_e32 v228, v224, v190
	v_add_u32_e32 v173, v173, v187
	v_add_u32_e32 v224, v224, v187
	ds_read_b128 v[174:177], v96
	ds_read_b128 v[204:207], v97
	ds_read_b128 v[208:211], v98
	ds_read_b128 v[212:215], v99
	ds_read_b128 v[216:219], v100
	ds_read_b128 v[220:223], v101
	ds_read_b128 v[230:233], v225
	ds_read_b128 v[234:237], v226
	ds_read_b128 v[238:241], v227
	ds_read_b128 v[242:245], v228
	ds_read_b128 v[246:249], v173
	ds_read_b128 v[250:253], v224
	s_cmp_eq_u32 s73, 0
	s_cselect_b64 s[78:79], -1, 0
	s_waitcnt lgkmcnt(11)
	v_mfma_f32_32x32x16_bf16 v[96:111], v[174:177], v[116:119], v[80:95]
	s_waitcnt lgkmcnt(10)
	v_mfma_f32_32x32x16_bf16 v[80:95], v[204:207], v[116:119], v[80:95]
	s_waitcnt lgkmcnt(9)
	v_mfma_f32_32x32x16_bf16 v[96:111], v[208:211], v[120:123], v[96:111]
	s_waitcnt lgkmcnt(8)
	v_mfma_f32_32x32x16_bf16 v[80:95], v[212:215], v[120:123], v[80:95]
	s_waitcnt lgkmcnt(7)
	v_mfma_f32_32x32x16_bf16 v[96:111], v[216:219], v[124:127], v[96:111]
	s_waitcnt lgkmcnt(6)
	v_mfma_f32_32x32x16_bf16 v[80:95], v[220:223], v[124:127], v[80:95]
	v_max_f32_e32 v173, v65, v65
	s_waitcnt lgkmcnt(5)
	v_mfma_f32_32x32x16_bf16 v[96:111], v[230:233], v[128:131], v[96:111]
	v_max_f32_e32 v174, v64, v64
	v_max_f32_e32 v173, v174, v173
	v_max3_f32 v173, v173, v66, v67
	v_max3_f32 v173, v173, v68, v69
	v_max3_f32 v173, v173, v70, v71
	v_max3_f32 v173, v173, v72, v73
	v_max3_f32 v173, v173, v74, v75
	s_waitcnt lgkmcnt(4)
	v_mfma_f32_32x32x16_bf16 v[80:95], v[234:237], v[128:131], v[80:95]
	v_max3_f32 v173, v173, v76, v77
	v_max3_f32 v173, v173, v78, v79
	v_max3_f32 v173, v173, v48, v49
	v_max3_f32 v173, v173, v50, v51
	v_max3_f32 v173, v173, v52, v53
	v_max3_f32 v173, v173, v54, v55
	v_max3_f32 v173, v173, v56, v57
	s_waitcnt lgkmcnt(3)
	v_mfma_f32_32x32x16_bf16 v[96:111], v[238:241], v[132:135], v[96:111]
	v_max3_f32 v173, v173, v58, v59
	v_max3_f32 v173, v173, v60, v61
	v_max3_f32 v204, v173, v62, v63
	v_cmp_lt_f32_e32 vcc, s29, v204
	s_or_b64 vcc, s[78:79], vcc
	s_waitcnt lgkmcnt(2)
	v_mfma_f32_32x32x16_bf16 v[80:95], v[242:245], v[132:135], v[80:95]
	s_waitcnt lgkmcnt(1)
	v_mfma_f32_32x32x16_bf16 v[96:111], v[246:249], v[136:139], v[96:111]
	s_waitcnt lgkmcnt(0)
	v_mfma_f32_32x32x16_bf16 v[80:95], v[250:253], v[136:139], v[80:95]
	s_cbranch_vccz .LBB0_450
	v_and_b32_e32 v153, 64, v172
	v_xor_b32_e32 v152, 32, v172
	v_add_u32_e32 v153, 64, v153
	v_cmp_lt_i32_e32 vcc, v152, v153
	v_max_f32_e32 v153, v204, v204
	v_mov_b32_e32 v155, 0
	v_cndmask_b32_e32 v152, v172, v152, vcc
	v_lshlrev_b32_e32 v152, 2, v152
	ds_bpermute_b32 v152, v152, v204
	v_mov_b32_e32 v204, 0
	s_waitcnt lgkmcnt(0)
	v_max_f32_e32 v152, v152, v152
	v_max_f32_e32 v152, v153, v152
	v_cmp_lt_f32_e32 vcc, s30, v152
	s_and_b64 s[18:19], s[78:79], vcc
	v_cmp_lt_f32_e32 vcc, s29, v152
	s_or_b64 s[78:79], vcc, s[18:19]
	s_and_saveexec_b64 s[18:19], s[78:79]
	v_add_f32_e32 v152, v203, v152
	v_cvt_pk_bf16_f32 v152, v152, 0
	v_lshlrev_b32_e32 v152, 16, v152
	v_sub_f32_e32 v204, v152, v203
	v_mov_b32_e32 v203, v152
	s_or_b64 exec, exec, s[18:19]
	v_exp_f32_e64 v152, -v204
	s_mov_b64 vcc, s[8:9]
	v_sub_f32_e32 v64, v64, v204
	v_sub_f32_e32 v65, v65, v204
	v_pk_mul_f32 v[46:47], v[46:47], v[152:153] op_sel_hi:[1,0]
	v_pk_mul_f32 v[44:45], v[44:45], v[152:153] op_sel_hi:[1,0]
	v_pk_mul_f32 v[42:43], v[42:43], v[152:153] op_sel_hi:[1,0]
	v_pk_mul_f32 v[40:41], v[40:41], v[152:153] op_sel_hi:[1,0]
	v_pk_mul_f32 v[38:39], v[38:39], v[152:153] op_sel_hi:[1,0]
	v_pk_mul_f32 v[36:37], v[36:37], v[152:153] op_sel_hi:[1,0]
	v_pk_mul_f32 v[34:35], v[34:35], v[152:153] op_sel_hi:[1,0]
	v_pk_mul_f32 v[32:33], v[32:33], v[152:153] op_sel_hi:[1,0]
	v_pk_mul_f32 v[30:31], v[30:31], v[152:153] op_sel_hi:[1,0]
	v_pk_mul_f32 v[28:29], v[28:29], v[152:153] op_sel_hi:[1,0]
	v_pk_mul_f32 v[26:27], v[26:27], v[152:153] op_sel_hi:[1,0]
	v_pk_mul_f32 v[24:25], v[24:25], v[152:153] op_sel_hi:[1,0]
	v_pk_mul_f32 v[22:23], v[22:23], v[152:153] op_sel_hi:[1,0]
	v_pk_mul_f32 v[20:21], v[20:21], v[152:153] op_sel_hi:[1,0]
	v_pk_mul_f32 v[18:19], v[18:19], v[152:153] op_sel_hi:[1,0]
	v_pk_mul_f32 v[16:17], v[16:17], v[152:153] op_sel_hi:[1,0]
	v_pk_mul_f32 v[14:15], v[14:15], v[152:153] op_sel_hi:[1,0]
	v_pk_mul_f32 v[12:13], v[12:13], v[152:153] op_sel_hi:[1,0]
	v_pk_mul_f32 v[10:11], v[10:11], v[152:153] op_sel_hi:[1,0]
	v_pk_mul_f32 v[8:9], v[8:9], v[152:153] op_sel_hi:[1,0]
	v_pk_mul_f32 v[6:7], v[6:7], v[152:153] op_sel_hi:[1,0]
	v_pk_mul_f32 v[4:5], v[4:5], v[152:153] op_sel_hi:[1,0]
	v_pk_mul_f32 v[2:3], v[2:3], v[152:153] op_sel_hi:[1,0]
	v_pk_mul_f32 v[0:1], v[0:1], v[152:153] op_sel_hi:[1,0]
	v_xor_b32_e32 v152, 0x80000000, v203
	v_sub_f32_e32 v66, v66, v204
	v_sub_f32_e32 v67, v67, v204
	v_sub_f32_e32 v68, v68, v204
	v_sub_f32_e32 v69, v69, v204
	v_sub_f32_e32 v70, v70, v204
	v_sub_f32_e32 v71, v71, v204
	v_sub_f32_e32 v72, v72, v204
	v_sub_f32_e32 v73, v73, v204
	v_sub_f32_e32 v74, v74, v204
	v_sub_f32_e32 v75, v75, v204
	v_sub_f32_e32 v76, v76, v204
	v_sub_f32_e32 v77, v77, v204
	v_sub_f32_e32 v78, v78, v204
	v_sub_f32_e32 v79, v79, v204
	v_sub_f32_e32 v48, v48, v204
	v_sub_f32_e32 v49, v49, v204
	v_sub_f32_e32 v50, v50, v204
	v_sub_f32_e32 v51, v51, v204
	v_sub_f32_e32 v52, v52, v204
	v_sub_f32_e32 v53, v53, v204
	v_sub_f32_e32 v54, v54, v204
	v_sub_f32_e32 v55, v55, v204
	v_sub_f32_e32 v56, v56, v204
	v_sub_f32_e32 v57, v57, v204
	v_sub_f32_e32 v58, v58, v204
	v_sub_f32_e32 v59, v59, v204
	v_sub_f32_e32 v60, v60, v204
	v_sub_f32_e32 v61, v61, v204
	v_sub_f32_e32 v62, v62, v204
	v_sub_f32_e32 v63, v63, v204
	v_cndmask_b32_sdwa v152, v113, v152, vcc dst_sel:DWORD dst_unused:UNUSED_PAD src0_sel:DWORD src1_sel:WORD_1
	v_mov_b32_e32 v154, 0
	v_mov_b32_e32 v153, 0
	s_branch .LBB0_451

.LBB0_455:
	s_or_b64 exec, exec, s[78:79]
	v_pk_add_f32 v[48:49], v[48:49], v[64:65]
	v_pk_add_f32 v[50:51], v[50:51], v[66:67]
	v_pk_add_f32 v[52:53], v[52:53], v[68:69]
	v_pk_add_f32 v[54:55], v[54:55], v[70:71]
	v_pk_add_f32 v[56:57], v[56:57], v[72:73]
	v_pk_add_f32 v[58:59], v[58:59], v[74:75]
	v_pk_add_f32 v[60:61], v[60:61], v[76:77]
	v_pk_add_f32 v[62:63], v[62:63], v[78:79]
	v_pk_add_f32 v[12:13], v[60:61], v[12:13]
	v_pk_add_f32 v[14:15], v[62:63], v[14:15]
	v_pk_add_f32 v[10:11], v[58:59], v[10:11]
	v_pk_add_f32 v[8:9], v[56:57], v[8:9]
	v_pk_add_f32 v[6:7], v[54:55], v[6:7]
	v_pk_add_f32 v[4:5], v[52:53], v[4:5]
	v_pk_add_f32 v[2:3], v[50:51], v[2:3]
	v_pk_add_f32 v[0:1], v[48:49], v[0:1]
.LBB0_456:
	s_or_b64 exec, exec, s[86:87]
	s_add_i32 s69, s73, 2
	s_cmp_lt_u32 s69, s70
	s_cselect_b64 s[18:19], -1, 0
	s_cmp_ge_u32 s69, s70
	s_cbranch_scc0 .LBB0_463
	s_cmp_ge_u32 s74, s70
	s_cbranch_scc0 .LBB0_466

.LBB0_460:
	s_sub_i32 s18, s14, 64
	s_mov_b32 s19, s15
	v_lshl_add_u64 v[226:227], s[18:19], 1, v[168:169]
	global_load_dwordx4 v[148:151], v[226:227], off

.LBB0_463:
	s_lshl_b32 s75, s68, 14
	v_add_u32_e32 v226, s75, v188
	s_waitcnt vmcnt(0)
	ds_write_b128 v226, v[144:147]
	s_and_saveexec_b64 s[68:69], s[6:7]
	v_add_u32_e32 v226, s75, v189
	ds_write_b128 v226, v[140:143]
	s_or_b64 exec, exec, s[68:69]
	s_cmp_ge_u32 s74, s70
	s_cbranch_scc1 .LBB0_458
.LBB0_466:
	s_and_b32 s68, s71, 0x2000
	v_add_u32_e32 v227, s68, v192
	v_add_u32_e32 v226, s68, v193
	s_waitcnt vmcnt(0)
	ds_write_b64 v227, v[148:149] offset:32768
	ds_write_b64 v226, v[150:151]
	s_add_i32 s68, s73, 3
	s_cmp_ge_u32 s68, s70
	s_cbranch_scc1 .LBB0_459
.LBB0_467:
	s_lshl_b64 s[68:69], s[14:15], 11
	v_lshl_add_u64 v[226:227], v[166:167], 0, s[68:69]
	global_load_dwordx4 v[144:147], v[226:227], off
	s_and_saveexec_b64 s[68:69], s[6:7]
	s_cbranch_execz .LBB0_469
	s_lshl_b64 s[78:79], s[14:15], 6
	v_lshl_add_u64 v[226:227], v[164:165], 0, s[78:79]
	global_load_dwordx4 v[140:143], v[226:227], off

.Lmo_437:
	s_and_b32 s68, s73, 1
	s_add_i32 s74, s73, 1
	s_lshl_b32 s69, s68, 13
	v_cmp_ge_i32_e32 vcc, s74, v197
	s_and_saveexec_b64 s[18:19], vcc
	s_xor_b64 s[86:87], exec, s[18:19]
	s_cbranch_execz .Lmo_445
	v_cmp_lt_i32_e32 vcc, s73, v197
	s_and_saveexec_b64 s[78:79], vcc
	s_cbranch_execz .Lmo_444
	v_max_f32_e32 v48, v97, v97
	v_max_f32_e32 v49, v96, v96
	v_max_f32_e32 v48, v49, v48
	v_max3_f32 v48, v48, v98, v99
	v_max3_f32 v48, v48, v100, v101
	v_max3_f32 v48, v48, v102, v103
	v_max3_f32 v48, v48, v104, v105
	v_max3_f32 v48, v48, v106, v107
	v_max3_f32 v48, v48, v108, v109
	v_max3_f32 v48, v48, v110, v111
	v_max3_f32 v48, v48, v80, v81
	v_max3_f32 v48, v48, v82, v83
	v_max3_f32 v48, v48, v84, v85
	v_max3_f32 v48, v48, v86, v87
	v_max3_f32 v48, v48, v88, v89
	v_max3_f32 v48, v48, v90, v91
	v_max3_f32 v48, v48, v92, v93
	s_cmp_eq_u32 s73, 0
	v_max3_f32 v48, v48, v94, v95
	s_cselect_b64 s[18:19], -1, 0
	v_cmp_lt_f32_e32 vcc, s29, v48
	s_or_b64 vcc, s[18:19], vcc
	s_cbranch_vccz .Lmo_443
	v_and_b32_e32 v50, 64, v172
	v_xor_b32_e32 v49, 32, v172
	v_add_u32_e32 v50, 64, v50
	v_cmp_lt_i32_e32 vcc, v49, v50
	v_mov_b32_e32 v155, 0
	s_nop 0
	v_cndmask_b32_e32 v49, v172, v49, vcc
	v_lshlrev_b32_e32 v49, 2, v49
	ds_bpermute_b32 v49, v49, v48
	v_max_f32_e32 v48, v48, v48
	s_waitcnt lgkmcnt(0)
	v_max_f32_e32 v49, v49, v49
	v_max_f32_e32 v49, v48, v49
	v_cmp_lt_f32_e32 vcc, s30, v49
	s_and_b64 s[18:19], s[18:19], vcc
	v_cmp_lt_f32_e32 vcc, s29, v49
	s_or_b64 vcc, vcc, s[18:19]
	v_mov_b32_e32 v48, 0
	s_and_saveexec_b64 s[18:19], vcc
	v_add_f32_e32 v48, v203, v49
	v_cvt_pk_bf16_f32 v48, v48, 0
	v_lshlrev_b32_e32 v49, 16, v48
	v_sub_f32_e32 v48, v49, v203
	v_mov_b32_e32 v203, v49
	s_or_b64 exec, exec, s[18:19]
	v_exp_f32_e64 v50, -v48
	s_mov_b64 vcc, s[8:9]
	v_sub_f32_e32 v111, v111, v48
	v_sub_f32_e32 v110, v110, v48
	v_sub_f32_e32 v109, v109, v48
	v_sub_f32_e32 v108, v108, v48
	v_sub_f32_e32 v107, v107, v48
	v_sub_f32_e32 v106, v106, v48
	v_sub_f32_e32 v105, v105, v48
	v_sub_f32_e32 v104, v104, v48
	v_sub_f32_e32 v103, v103, v48
	v_sub_f32_e32 v102, v102, v48
	v_sub_f32_e32 v101, v101, v48
	v_sub_f32_e32 v100, v100, v48
	v_sub_f32_e32 v99, v99, v48
	v_sub_f32_e32 v98, v98, v48
	v_sub_f32_e32 v97, v97, v48
	v_sub_f32_e32 v96, v96, v48
	v_sub_f32_e32 v95, v95, v48
	v_sub_f32_e32 v94, v94, v48
	v_sub_f32_e32 v93, v93, v48
	v_sub_f32_e32 v92, v92, v48
	v_sub_f32_e32 v91, v91, v48
	v_sub_f32_e32 v90, v90, v48
	v_sub_f32_e32 v89, v89, v48
	v_sub_f32_e32 v88, v88, v48
	v_sub_f32_e32 v87, v87, v48
	v_sub_f32_e32 v86, v86, v48
	v_sub_f32_e32 v85, v85, v48
	v_sub_f32_e32 v84, v84, v48
	v_sub_f32_e32 v83, v83, v48
	v_sub_f32_e32 v82, v82, v48
	v_sub_f32_e32 v81, v81, v48
	v_sub_f32_e32 v80, v80, v48
	v_xor_b32_e32 v48, 0x80000000, v203
	v_pk_mul_f32 v[46:47], v[46:47], v[50:51] op_sel_hi:[1,0]
	v_pk_mul_f32 v[44:45], v[44:45], v[50:51] op_sel_hi:[1,0]
	v_pk_mul_f32 v[42:43], v[42:43], v[50:51] op_sel_hi:[1,0]
	v_pk_mul_f32 v[40:41], v[40:41], v[50:51] op_sel_hi:[1,0]
	v_pk_mul_f32 v[38:39], v[38:39], v[50:51] op_sel_hi:[1,0]
	v_pk_mul_f32 v[36:37], v[36:37], v[50:51] op_sel_hi:[1,0]
	v_pk_mul_f32 v[34:35], v[34:35], v[50:51] op_sel_hi:[1,0]
	v_pk_mul_f32 v[32:33], v[32:33], v[50:51] op_sel_hi:[1,0]
	v_pk_mul_f32 v[30:31], v[30:31], v[50:51] op_sel_hi:[1,0]
	v_pk_mul_f32 v[28:29], v[28:29], v[50:51] op_sel_hi:[1,0]
	v_pk_mul_f32 v[26:27], v[26:27], v[50:51] op_sel_hi:[1,0]
	v_pk_mul_f32 v[24:25], v[24:25], v[50:51] op_sel_hi:[1,0]
	v_pk_mul_f32 v[22:23], v[22:23], v[50:51] op_sel_hi:[1,0]
	v_pk_mul_f32 v[20:21], v[20:21], v[50:51] op_sel_hi:[1,0]
	v_pk_mul_f32 v[18:19], v[18:19], v[50:51] op_sel_hi:[1,0]
	v_pk_mul_f32 v[16:17], v[16:17], v[50:51] op_sel_hi:[1,0]
	v_pk_mul_f32 v[14:15], v[14:15], v[50:51] op_sel_hi:[1,0]
	v_pk_mul_f32 v[12:13], v[12:13], v[50:51] op_sel_hi:[1,0]
	v_pk_mul_f32 v[10:11], v[10:11], v[50:51] op_sel_hi:[1,0]
	v_pk_mul_f32 v[8:9], v[8:9], v[50:51] op_sel_hi:[1,0]
	v_pk_mul_f32 v[6:7], v[6:7], v[50:51] op_sel_hi:[1,0]
	v_pk_mul_f32 v[4:5], v[4:5], v[50:51] op_sel_hi:[1,0]
	v_pk_mul_f32 v[2:3], v[2:3], v[50:51] op_sel_hi:[1,0]
	v_pk_mul_f32 v[0:1], v[0:1], v[50:51] op_sel_hi:[1,0]
	v_cndmask_b32_sdwa v152, v113, v48, vcc dst_sel:DWORD dst_unused:UNUSED_PAD src0_sel:DWORD src1_sel:WORD_1
	v_mov_b32_e32 v154, 0
	v_mov_b32_e32 v153, 0
.Lmo_443:
	v_add_u32_e32 v68, s69, v198
	v_add_u32_e32 v69, v68, v199
	ds_read_b128 v[64:67], v69 offset:32768
	v_exp_f32_e32 v108, v108
	v_exp_f32_e32 v92, v92
	v_exp_f32_e32 v109, v109
	v_exp_f32_e32 v93, v93
	v_exp_f32_e32 v110, v110
	v_exp_f32_e32 v94, v94
	v_exp_f32_e32 v111, v111
	v_exp_f32_e32 v95, v95
	v_exp_f32_e32 v96, v96
	v_exp_f32_e32 v97, v97
	v_exp_f32_e32 v98, v98
	v_exp_f32_e32 v99, v99
	v_exp_f32_e32 v100, v100
	v_exp_f32_e32 v101, v101
	v_exp_f32_e32 v102, v102
	v_exp_f32_e32 v103, v103
	v_pk_add_f32 v[60:61], v[92:93], v[108:109]
	v_pk_add_f32 v[62:63], v[94:95], v[110:111]
	v_pk_add_f32 v[12:13], v[60:61], v[12:13]
	v_pk_add_f32 v[14:15], v[62:63], v[14:15]
	v_cvt_pk_bf16_f32 v60, v96, v97
	v_cvt_pk_bf16_f32 v61, v98, v99
	v_cvt_pk_bf16_f32 v62, v100, v101
	v_cvt_pk_bf16_f32 v63, v102, v103
	v_exp_f32_e32 v104, v104
	v_exp_f32_e32 v88, v88
	s_waitcnt lgkmcnt(0)
	v_mfma_f32_32x32x16_bf16 v[32:47], v[64:67], v[60:63], v[32:47]
	ds_read_b128 v[64:67], v69 offset:36864
	v_exp_f32_e32 v105, v105
	v_exp_f32_e32 v89, v89
	v_exp_f32_e32 v106, v106
	v_exp_f32_e32 v90, v90
	v_exp_f32_e32 v107, v107
	v_exp_f32_e32 v91, v91
	s_waitcnt lgkmcnt(0)
	v_mfma_f32_32x32x16_bf16 v[16:31], v[64:67], v[60:63], v[16:31]
	v_add_u32_e32 v64, v68, v200
	ds_read_b128 v[60:63], v64 offset:32768
	v_add_f32_e64 v56, v88, v104
	v_add_f32_e64 v57, v89, v105
	v_add_f32_e64 v58, v90, v106
	v_add_f32_e64 v59, v91, v107
	v_pk_add_f32 v[8:9], v[56:57], v[8:9]
	v_pk_add_f32 v[10:11], v[58:59], v[10:11]
	v_cvt_pk_bf16_f32 v56, v104, v105
	v_cvt_pk_bf16_f32 v57, v106, v107
	v_cvt_pk_bf16_f32 v58, v108, v109
	v_cvt_pk_bf16_f32 v59, v110, v111
	v_exp_f32_e32 v84, v84
	v_exp_f32_e32 v85, v85
	s_waitcnt lgkmcnt(0)
	v_mfma_f32_32x32x16_bf16 v[32:47], v[60:63], v[56:59], v[32:47]
	ds_read_b128 v[60:63], v64 offset:36864
	v_exp_f32_e32 v86, v86
	v_exp_f32_e32 v87, v87
	v_exp_f32_e32 v80, v80
	v_exp_f32_e32 v81, v81
	v_exp_f32_e32 v82, v82
	v_exp_f32_e32 v83, v83
	s_waitcnt lgkmcnt(0)
	v_mfma_f32_32x32x16_bf16 v[16:31], v[60:63], v[56:59], v[16:31]
	v_add_u32_e32 v60, v68, v201
	ds_read_b128 v[56:59], v60 offset:32768
	v_add_f32_e64 v52, v84, v100
	v_add_f32_e64 v53, v85, v101
	v_add_f32_e64 v54, v86, v102
	v_add_f32_e64 v55, v87, v103
	v_pk_add_f32 v[4:5], v[52:53], v[4:5]
	v_pk_add_f32 v[6:7], v[54:55], v[6:7]
	v_cvt_pk_bf16_f32 v52, v80, v81
	v_cvt_pk_bf16_f32 v53, v82, v83
	v_cvt_pk_bf16_f32 v54, v84, v85
	v_cvt_pk_bf16_f32 v55, v86, v87
	v_pk_add_f32 v[48:49], v[80:81], v[96:97]
	v_pk_add_f32 v[50:51], v[82:83], v[98:99]
	s_waitcnt lgkmcnt(0)
	v_mfma_f32_32x32x16_bf16 v[32:47], v[56:59], v[52:55], v[32:47]
	ds_read_b128 v[56:59], v60 offset:36864
	v_add_f32_e64 v2, v50, v2
	v_add_f32_e64 v3, v51, v3
	v_add_f32_e64 v0, v48, v0
	v_add_f32_e64 v1, v49, v1
	v_cvt_pk_bf16_f32 v48, v88, v89
	v_cvt_pk_bf16_f32 v49, v90, v91
	v_cvt_pk_bf16_f32 v50, v92, v93
	v_cvt_pk_bf16_f32 v51, v94, v95
	s_waitcnt lgkmcnt(0)
	v_mfma_f32_32x32x16_bf16 v[16:31], v[56:59], v[52:55], v[16:31]
	v_add_u32_e32 v56, v68, v202
	ds_read_b128 v[52:55], v56 offset:32768
	s_waitcnt lgkmcnt(0)
	v_mfma_f32_32x32x16_bf16 v[32:47], v[52:55], v[48:51], v[32:47]
	ds_read_b128 v[52:55], v56 offset:36864
	s_waitcnt lgkmcnt(0)
	v_mfma_f32_32x32x16_bf16 v[16:31], v[52:55], v[48:51], v[16:31]

.Lmo_445:
	s_andn2_saveexec_b64 s[86:87], s[86:87]
	s_cbranch_execz .Lmo_456
	v_mfma_f32_32x32x16_bf16 v[48:63], v[112:115], v[152:155], 0
	s_and_b32 s18, s72, 0x4000
	v_or_b32_e32 v173, s18, v194
	v_or_b32_e32 v224, 0x2000, v173
	v_add_u32_e32 v64, v173, v186
	v_add_u32_e32 v65, v224, v186
	v_add_u32_e32 v66, v173, v184
	v_add_u32_e32 v67, v224, v184
	v_add_u32_e32 v68, v173, v183
	v_add_u32_e32 v69, v224, v183
	v_add_u32_e32 v225, v173, v191
	v_add_u32_e32 v226, v224, v191
	v_add_u32_e32 v227, v173, v190
	v_add_u32_e32 v228, v224, v190
	v_add_u32_e32 v173, v173, v187
	v_add_u32_e32 v224, v224, v187
	ds_read_b128 v[174:177], v64
	ds_read_b128 v[204:207], v65
	ds_read_b128 v[208:211], v66
	ds_read_b128 v[212:215], v67
	ds_read_b128 v[216:219], v68
	ds_read_b128 v[220:223], v69
	ds_read_b128 v[230:233], v225
	ds_read_b128 v[234:237], v226
	ds_read_b128 v[238:241], v227
	ds_read_b128 v[242:245], v228
	ds_read_b128 v[246:249], v173
	ds_read_b128 v[250:253], v224
	s_cmp_eq_u32 s73, 0
	s_cselect_b64 s[78:79], -1, 0
	s_waitcnt lgkmcnt(11)
	v_mfma_f32_32x32x16_bf16 v[64:79], v[174:177], v[116:119], v[48:63]
	s_waitcnt lgkmcnt(10)
	v_mfma_f32_32x32x16_bf16 v[48:63], v[204:207], v[116:119], v[48:63]
	s_waitcnt lgkmcnt(9)
	v_mfma_f32_32x32x16_bf16 v[64:79], v[208:211], v[120:123], v[64:79]
	s_waitcnt lgkmcnt(8)
	v_mfma_f32_32x32x16_bf16 v[48:63], v[212:215], v[120:123], v[48:63]
	s_waitcnt lgkmcnt(7)
	v_mfma_f32_32x32x16_bf16 v[64:79], v[216:219], v[124:127], v[64:79]
	s_waitcnt lgkmcnt(6)
	v_mfma_f32_32x32x16_bf16 v[48:63], v[220:223], v[124:127], v[48:63]
	v_max_f32_e32 v173, v97, v97
	s_waitcnt lgkmcnt(5)
	v_mfma_f32_32x32x16_bf16 v[64:79], v[230:233], v[128:131], v[64:79]
	v_max_f32_e32 v174, v96, v96
	v_max_f32_e32 v173, v174, v173
	v_max3_f32 v173, v173, v98, v99
	v_max3_f32 v173, v173, v100, v101
	v_max3_f32 v173, v173, v102, v103
	v_max3_f32 v173, v173, v104, v105
	v_max3_f32 v173, v173, v106, v107
	s_waitcnt lgkmcnt(4)
	v_mfma_f32_32x32x16_bf16 v[48:63], v[234:237], v[128:131], v[48:63]
	v_max3_f32 v173, v173, v108, v109
	v_max3_f32 v173, v173, v110, v111
	v_max3_f32 v173, v173, v80, v81
	v_max3_f32 v173, v173, v82, v83
	v_max3_f32 v173, v173, v84, v85
	v_max3_f32 v173, v173, v86, v87
	v_max3_f32 v173, v173, v88, v89
	s_waitcnt lgkmcnt(3)
	v_mfma_f32_32x32x16_bf16 v[64:79], v[238:241], v[132:135], v[64:79]
	v_max3_f32 v173, v173, v90, v91
	v_max3_f32 v173, v173, v92, v93
	v_max3_f32 v204, v173, v94, v95
	v_cmp_lt_f32_e32 vcc, s29, v204
	s_or_b64 vcc, s[78:79], vcc
	s_waitcnt lgkmcnt(2)
	v_mfma_f32_32x32x16_bf16 v[48:63], v[242:245], v[132:135], v[48:63]
	s_waitcnt lgkmcnt(1)
	v_mfma_f32_32x32x16_bf16 v[64:79], v[246:249], v[136:139], v[64:79]
	s_waitcnt lgkmcnt(0)
	v_mfma_f32_32x32x16_bf16 v[48:63], v[250:253], v[136:139], v[48:63]
	s_cbranch_vccz .Lmo_450
	v_and_b32_e32 v153, 64, v172
	v_xor_b32_e32 v152, 32, v172
	v_add_u32_e32 v153, 64, v153
	v_cmp_lt_i32_e32 vcc, v152, v153
	v_max_f32_e32 v153, v204, v204
	v_mov_b32_e32 v155, 0
	v_cndmask_b32_e32 v152, v172, v152, vcc
	v_lshlrev_b32_e32 v152, 2, v152
	ds_bpermute_b32 v152, v152, v204
	v_mov_b32_e32 v204, 0
	s_waitcnt lgkmcnt(0)
	v_max_f32_e32 v152, v152, v152
	v_max_f32_e32 v152, v153, v152
	v_cmp_lt_f32_e32 vcc, s30, v152
	s_and_b64 s[18:19], s[78:79], vcc
	v_cmp_lt_f32_e32 vcc, s29, v152
	s_or_b64 s[78:79], vcc, s[18:19]
	s_and_saveexec_b64 s[18:19], s[78:79]
	v_add_f32_e32 v152, v203, v152
	v_cvt_pk_bf16_f32 v152, v152, 0
	v_lshlrev_b32_e32 v152, 16, v152
	v_sub_f32_e32 v204, v152, v203
	v_mov_b32_e32 v203, v152
	s_or_b64 exec, exec, s[18:19]
	v_exp_f32_e64 v152, -v204
	s_mov_b64 vcc, s[8:9]
	v_sub_f32_e32 v96, v96, v204
	v_sub_f32_e32 v97, v97, v204
	v_pk_mul_f32 v[46:47], v[46:47], v[152:153] op_sel_hi:[1,0]
	v_pk_mul_f32 v[44:45], v[44:45], v[152:153] op_sel_hi:[1,0]
	v_pk_mul_f32 v[42:43], v[42:43], v[152:153] op_sel_hi:[1,0]
	v_pk_mul_f32 v[40:41], v[40:41], v[152:153] op_sel_hi:[1,0]
	v_pk_mul_f32 v[38:39], v[38:39], v[152:153] op_sel_hi:[1,0]
	v_pk_mul_f32 v[36:37], v[36:37], v[152:153] op_sel_hi:[1,0]
	v_pk_mul_f32 v[34:35], v[34:35], v[152:153] op_sel_hi:[1,0]
	v_pk_mul_f32 v[32:33], v[32:33], v[152:153] op_sel_hi:[1,0]
	v_pk_mul_f32 v[30:31], v[30:31], v[152:153] op_sel_hi:[1,0]
	v_pk_mul_f32 v[28:29], v[28:29], v[152:153] op_sel_hi:[1,0]
	v_pk_mul_f32 v[26:27], v[26:27], v[152:153] op_sel_hi:[1,0]
	v_pk_mul_f32 v[24:25], v[24:25], v[152:153] op_sel_hi:[1,0]
	v_pk_mul_f32 v[22:23], v[22:23], v[152:153] op_sel_hi:[1,0]
	v_pk_mul_f32 v[20:21], v[20:21], v[152:153] op_sel_hi:[1,0]
	v_pk_mul_f32 v[18:19], v[18:19], v[152:153] op_sel_hi:[1,0]
	v_pk_mul_f32 v[16:17], v[16:17], v[152:153] op_sel_hi:[1,0]
	v_pk_mul_f32 v[14:15], v[14:15], v[152:153] op_sel_hi:[1,0]
	v_pk_mul_f32 v[12:13], v[12:13], v[152:153] op_sel_hi:[1,0]
	v_pk_mul_f32 v[10:11], v[10:11], v[152:153] op_sel_hi:[1,0]
	v_pk_mul_f32 v[8:9], v[8:9], v[152:153] op_sel_hi:[1,0]
	v_pk_mul_f32 v[6:7], v[6:7], v[152:153] op_sel_hi:[1,0]
	v_pk_mul_f32 v[4:5], v[4:5], v[152:153] op_sel_hi:[1,0]
	v_pk_mul_f32 v[2:3], v[2:3], v[152:153] op_sel_hi:[1,0]
	v_pk_mul_f32 v[0:1], v[0:1], v[152:153] op_sel_hi:[1,0]
	v_xor_b32_e32 v152, 0x80000000, v203
	v_sub_f32_e32 v98, v98, v204
	v_sub_f32_e32 v99, v99, v204
	v_sub_f32_e32 v100, v100, v204
	v_sub_f32_e32 v101, v101, v204
	v_sub_f32_e32 v102, v102, v204
	v_sub_f32_e32 v103, v103, v204
	v_sub_f32_e32 v104, v104, v204
	v_sub_f32_e32 v105, v105, v204
	v_sub_f32_e32 v106, v106, v204
	v_sub_f32_e32 v107, v107, v204
	v_sub_f32_e32 v108, v108, v204
	v_sub_f32_e32 v109, v109, v204
	v_sub_f32_e32 v110, v110, v204
	v_sub_f32_e32 v111, v111, v204
	v_sub_f32_e32 v80, v80, v204
	v_sub_f32_e32 v81, v81, v204
	v_sub_f32_e32 v82, v82, v204
	v_sub_f32_e32 v83, v83, v204
	v_sub_f32_e32 v84, v84, v204
	v_sub_f32_e32 v85, v85, v204
	v_sub_f32_e32 v86, v86, v204
	v_sub_f32_e32 v87, v87, v204
	v_sub_f32_e32 v88, v88, v204
	v_sub_f32_e32 v89, v89, v204
	v_sub_f32_e32 v90, v90, v204
	v_sub_f32_e32 v91, v91, v204
	v_sub_f32_e32 v92, v92, v204
	v_sub_f32_e32 v93, v93, v204
	v_sub_f32_e32 v94, v94, v204
	v_sub_f32_e32 v95, v95, v204
	v_cndmask_b32_sdwa v152, v113, v152, vcc dst_sel:DWORD dst_unused:UNUSED_PAD src0_sel:DWORD src1_sel:WORD_1
	v_mov_b32_e32 v154, 0
	v_mov_b32_e32 v153, 0
	s_branch .Lmo_451

.Lmo_451:
	v_add_u32_e32 v173, s69, v198
	v_add_u32_e32 v205, v173, v199
	ds_read_b128 v[174:177], v205 offset:32768
	ds_read_b128 v[210:213], v205 offset:36864
	v_exp_f32_e32 v96, v96
	v_exp_f32_e32 v97, v97
	v_exp_f32_e32 v98, v98
	v_exp_f32_e32 v99, v99
	v_exp_f32_e32 v100, v100
	v_exp_f32_e32 v101, v101
	v_exp_f32_e32 v102, v102
	v_exp_f32_e32 v103, v103
	v_cvt_pk_bf16_f32 v206, v96, v97
	v_cvt_pk_bf16_f32 v207, v98, v99
	v_cvt_pk_bf16_f32 v208, v100, v101
	v_cvt_pk_bf16_f32 v209, v102, v103
	v_add_u32_e32 v205, v173, v200
	v_exp_f32_e32 v104, v104
	s_waitcnt lgkmcnt(1)
	v_mfma_f32_32x32x16_bf16 v[32:47], v[174:177], v[206:209], v[32:47]
	ds_read_b128 v[174:177], v205 offset:32768
	v_exp_f32_e32 v105, v105
	v_exp_f32_e32 v106, v106
	v_exp_f32_e32 v107, v107
	v_exp_f32_e32 v108, v108
	v_exp_f32_e32 v109, v109
	v_exp_f32_e32 v110, v110
	s_waitcnt lgkmcnt(1)
	v_mfma_f32_32x32x16_bf16 v[16:31], v[210:213], v[206:209], v[16:31]
	ds_read_b128 v[210:213], v205 offset:36864
	v_exp_f32_e32 v111, v111
	v_cvt_pk_bf16_f32 v206, v104, v105
	v_cvt_pk_bf16_f32 v207, v106, v107
	v_cvt_pk_bf16_f32 v208, v108, v109
	v_cvt_pk_bf16_f32 v209, v110, v111
	v_add_u32_e32 v205, v173, v201
	v_exp_f32_e32 v80, v80
	s_waitcnt lgkmcnt(1)
	v_mfma_f32_32x32x16_bf16 v[32:47], v[174:177], v[206:209], v[32:47]
	ds_read_b128 v[174:177], v205 offset:32768
	v_exp_f32_e32 v81, v81
	v_exp_f32_e32 v82, v82
	v_exp_f32_e32 v83, v83
	v_exp_f32_e32 v84, v84
	v_exp_f32_e32 v85, v85
	v_exp_f32_e32 v86, v86
	s_waitcnt lgkmcnt(1)
	v_mfma_f32_32x32x16_bf16 v[16:31], v[210:213], v[206:209], v[16:31]
	ds_read_b128 v[210:213], v205 offset:36864
	v_exp_f32_e32 v87, v87
	v_cvt_pk_bf16_f32 v206, v80, v81
	v_cvt_pk_bf16_f32 v207, v82, v83
	v_cvt_pk_bf16_f32 v208, v84, v85
	v_cvt_pk_bf16_f32 v209, v86, v87
	v_add_u32_e32 v173, v173, v202
	v_exp_f32_e32 v88, v88
	s_waitcnt lgkmcnt(1)
	v_mfma_f32_32x32x16_bf16 v[32:47], v[174:177], v[206:209], v[32:47]
	ds_read_b128 v[174:177], v173 offset:32768
	v_exp_f32_e32 v89, v89
	v_exp_f32_e32 v90, v90
	v_exp_f32_e32 v91, v91
	v_exp_f32_e32 v92, v92
	v_exp_f32_e32 v93, v93
	v_exp_f32_e32 v94, v94
	s_waitcnt lgkmcnt(1)
	v_mfma_f32_32x32x16_bf16 v[16:31], v[210:213], v[206:209], v[16:31]
	ds_read_b128 v[210:213], v173 offset:36864
	v_exp_f32_e32 v95, v95
	v_cvt_pk_bf16_f32 v206, v88, v89
	v_cvt_pk_bf16_f32 v207, v90, v91
	v_cvt_pk_bf16_f32 v208, v92, v93
	v_cvt_pk_bf16_f32 v209, v94, v95
	v_cmp_neq_f32_e32 vcc, 0, v204
	s_waitcnt lgkmcnt(1)
	v_mfma_f32_32x32x16_bf16 v[32:47], v[174:177], v[206:209], v[32:47]
	s_waitcnt lgkmcnt(0)
	v_mfma_f32_32x32x16_bf16 v[16:31], v[210:213], v[206:209], v[16:31]
	s_cbranch_vccz .Lmo_453
	v_sub_f32_e32 v79, v79, v204
	v_sub_f32_e32 v78, v78, v204
	v_sub_f32_e32 v77, v77, v204
	v_sub_f32_e32 v76, v76, v204
	v_sub_f32_e32 v75, v75, v204
	v_sub_f32_e32 v74, v74, v204
	v_sub_f32_e32 v73, v73, v204
	v_sub_f32_e32 v72, v72, v204
	v_sub_f32_e32 v71, v71, v204
	v_sub_f32_e32 v70, v70, v204
	v_sub_f32_e32 v69, v69, v204
	v_sub_f32_e32 v68, v68, v204
	v_sub_f32_e32 v67, v67, v204
	v_sub_f32_e32 v66, v66, v204
	v_sub_f32_e32 v65, v65, v204
	v_sub_f32_e32 v64, v64, v204
	v_sub_f32_e32 v63, v63, v204
	v_sub_f32_e32 v62, v62, v204
	v_sub_f32_e32 v61, v61, v204
	v_sub_f32_e32 v60, v60, v204
	v_sub_f32_e32 v59, v59, v204
	v_sub_f32_e32 v58, v58, v204
	v_sub_f32_e32 v57, v57, v204
	v_sub_f32_e32 v56, v56, v204
	v_sub_f32_e32 v55, v55, v204
	v_sub_f32_e32 v54, v54, v204
	v_sub_f32_e32 v53, v53, v204
	v_sub_f32_e32 v52, v52, v204
	v_sub_f32_e32 v51, v51, v204
	v_sub_f32_e32 v50, v50, v204
	v_sub_f32_e32 v49, v49, v204
	v_sub_f32_e32 v48, v48, v204
.Lmo_453:
	s_add_i32 s18, s14, 0xffffffbf
	v_cmp_gt_i32_e32 vcc, s18, v161
	s_and_saveexec_b64 s[78:79], vcc
	s_cbranch_execz .Lmo_455
	v_add_u32_e32 v173, s14, v195
	v_add_u32_e32 v174, 0xffffff80, v173
	v_cmp_lt_i32_e32 vcc, v174, v162
	s_nop 1
	v_cndmask_b32_e32 v65, v181, v65, vcc
	v_cmp_le_i32_e32 vcc, v174, v162
	s_nop 1
	v_cndmask_b32_e32 v64, v181, v64, vcc
	v_cmp_lt_i32_e32 vcc, v174, v196
	s_nop 1
	v_cndmask_b32_e32 v49, v181, v49, vcc
	v_cmp_le_i32_e32 vcc, v174, v196
	v_add_u32_e32 v174, 0xffffff82, v173
	s_nop 0
	v_cndmask_b32_e32 v48, v181, v48, vcc
	v_cmp_le_i32_e32 vcc, v174, v162
	s_nop 1
	v_cndmask_b32_e32 v66, v181, v66, vcc
	v_cmp_le_i32_e32 vcc, v174, v196
	v_add_u32_e32 v174, 0xffffff83, v173
	s_nop 0
	v_cndmask_b32_e32 v50, v181, v50, vcc
	v_cmp_le_i32_e32 vcc, v174, v162
	s_nop 1
	v_cndmask_b32_e32 v67, v181, v67, vcc
	v_cmp_le_i32_e32 vcc, v174, v196
	v_add_u32_e32 v174, 0xffffff88, v173
	s_nop 0
	v_cndmask_b32_e32 v51, v181, v51, vcc
	v_cmp_le_i32_e32 vcc, v174, v162
	s_nop 1
	v_cndmask_b32_e32 v68, v181, v68, vcc
	v_cmp_le_i32_e32 vcc, v174, v196
	v_add_u32_e32 v174, 0xffffff89, v173
	s_nop 0
	v_cndmask_b32_e32 v52, v181, v52, vcc
	v_cmp_le_i32_e32 vcc, v174, v162
	s_nop 1
	v_cndmask_b32_e32 v69, v181, v69, vcc
	v_cmp_le_i32_e32 vcc, v174, v196
	v_add_u32_e32 v174, 0xffffff8a, v173
	s_nop 0
	v_cndmask_b32_e32 v53, v181, v53, vcc
	v_cmp_le_i32_e32 vcc, v174, v162
	s_nop 1
	v_cndmask_b32_e32 v70, v181, v70, vcc
	v_cmp_le_i32_e32 vcc, v174, v196
	v_add_u32_e32 v174, 0xffffff8b, v173
	s_nop 0
	v_cndmask_b32_e32 v54, v181, v54, vcc
	v_cmp_le_i32_e32 vcc, v174, v162
	s_nop 1
	v_cndmask_b32_e32 v71, v181, v71, vcc
	v_cmp_le_i32_e32 vcc, v174, v196
	v_add_u32_e32 v174, 0xffffff90, v173
	s_nop 0
	v_cndmask_b32_e32 v55, v181, v55, vcc
	v_cmp_le_i32_e32 vcc, v174, v162
	s_nop 1
	v_cndmask_b32_e32 v72, v181, v72, vcc
	v_cmp_le_i32_e32 vcc, v174, v196
	v_add_u32_e32 v174, 0xffffff91, v173
	s_nop 0
	v_cndmask_b32_e32 v56, v181, v56, vcc
	v_cmp_le_i32_e32 vcc, v174, v162
	s_nop 1
	v_cndmask_b32_e32 v73, v181, v73, vcc
	v_cmp_le_i32_e32 vcc, v174, v196
	v_add_u32_e32 v174, 0xffffff92, v173
	s_nop 0
	v_cndmask_b32_e32 v57, v181, v57, vcc
	v_cmp_le_i32_e32 vcc, v174, v162
	s_nop 1
	v_cndmask_b32_e32 v74, v181, v74, vcc
	v_cmp_le_i32_e32 vcc, v174, v196
	v_add_u32_e32 v174, 0xffffff93, v173
	s_nop 0
	v_cndmask_b32_e32 v58, v181, v58, vcc
	v_cmp_le_i32_e32 vcc, v174, v162
	s_nop 1
	v_cndmask_b32_e32 v75, v181, v75, vcc
	v_cmp_le_i32_e32 vcc, v174, v196
	v_add_u32_e32 v174, 0xffffff98, v173
	s_nop 0
	v_cndmask_b32_e32 v59, v181, v59, vcc
	v_cmp_le_i32_e32 vcc, v174, v162
	s_nop 1
	v_cndmask_b32_e32 v76, v181, v76, vcc
	v_cmp_le_i32_e32 vcc, v174, v196
	v_add_u32_e32 v174, 0xffffff99, v173
	s_nop 0
	v_cndmask_b32_e32 v60, v181, v60, vcc
	v_cmp_le_i32_e32 vcc, v174, v162
	s_nop 1
	v_cndmask_b32_e32 v77, v181, v77, vcc
	v_cmp_le_i32_e32 vcc, v174, v196
	v_add_u32_e32 v174, 0xffffff9a, v173
	v_add_u32_e32 v173, 0xffffff9b, v173
	v_cndmask_b32_e32 v61, v181, v61, vcc
	v_cmp_le_i32_e32 vcc, v174, v162
	s_nop 1
	v_cndmask_b32_e32 v78, v181, v78, vcc
	v_cmp_le_i32_e32 vcc, v174, v196
	s_nop 1
	v_cndmask_b32_e32 v62, v181, v62, vcc
	v_cmp_le_i32_e32 vcc, v173, v162
	s_nop 1
	v_cndmask_b32_e32 v79, v181, v79, vcc
	v_cmp_le_i32_e32 vcc, v173, v196
	s_nop 1
	v_cndmask_b32_e32 v63, v181, v63, vcc
.Lmo_455:
	s_or_b64 exec, exec, s[78:79]
	v_pk_add_f32 v[80:81], v[80:81], v[96:97]
	v_pk_add_f32 v[82:83], v[82:83], v[98:99]
	v_pk_add_f32 v[84:85], v[84:85], v[100:101]
	v_pk_add_f32 v[86:87], v[86:87], v[102:103]
	v_pk_add_f32 v[88:89], v[88:89], v[104:105]
	v_pk_add_f32 v[90:91], v[90:91], v[106:107]
	v_pk_add_f32 v[92:93], v[92:93], v[108:109]
	v_pk_add_f32 v[94:95], v[94:95], v[110:111]
	v_pk_add_f32 v[12:13], v[92:93], v[12:13]
	v_pk_add_f32 v[14:15], v[94:95], v[14:15]
	v_pk_add_f32 v[10:11], v[90:91], v[10:11]
	v_pk_add_f32 v[8:9], v[88:89], v[8:9]
	v_pk_add_f32 v[6:7], v[86:87], v[6:7]
	v_pk_add_f32 v[4:5], v[84:85], v[4:5]
	v_pk_add_f32 v[2:3], v[82:83], v[2:3]
	v_pk_add_f32 v[0:1], v[80:81], v[0:1]
